# lever 8/6.4: sparse-attention selected pass leads each segment with its first three K-fragment LDS reads (issued right after the barrier, before the staging loads and selection-bit test)
# speedup vs baseline: 1.0013x; 1.0013x over previous
; DI int crow(int i, int h) { return (i & 3) + 8 * (i >> 2) + 4 * h; }
; template <int MODE> ...
;     ...
;   auto body = [&](const int kb, const char* Ks, const char* Vs) {
;     bool bit = true;
;     if (MODE == 2) { unsigned w = (kb < 32) ? s0 : (kb < 64) ? s1 : (kb < 96) ? s2 : s3; bit = ((w >> (kb & 31)) & 1u) != 0; }
;     if (MODE != 2 || __any(bit)) {
;       f32x16 acc = scores_lds(Ks, half, qf, r, h);
;       const int key0 = kb * 64 + half * 32;
;       bool full;
;       if (MODE <= 1) full = (16 * (key0 + 31) + 31) <= t0;
;       else if (MODE == 2) full = (key0 + 31) <= t0;
;       else full = ((key0 + 31) <= t0) && (key0 >= (t0 + 31 - 511));
;       if (!full) {
; #pragma unroll
;         for (int i = 0; i < 16; ++i) {
;           const int key = key0 + crow(i, h);
;           bool v;
;           if (MODE <= 1) v = (16 * key + 31) <= t; else if (MODE == 2) v = key <= t; else v = (key <= t) && ((t - key) < 512);
;           acc[i] = v ? acc[i] : -1e30f;
;         }
;       }
;     ...
;     if (kb + 2 <= kb1) stage_load<NEEDV>(sr2, K, VT, ldvt, kb + 2, tid);
;     body(kb, buf0, buf0 + KS_BYTES);
.LBB0_161:
	ds_read_b128 v[238:241], v181
	ds_read_b128 v[242:245], v181 offset:32
	ds_read_b128 v[246:249], v181 offset:64
	s_add_i32 s14, s13, -1
	s_cmp_gt_u32 s14, s12
	s_cbranch_scc1 .LBB0_163
	v_add_co_u32_e32 v70, vcc, 0xffffc000, v172
	s_sub_i32 s18, s10, 64
	s_nop 0
	v_addc_co_u32_e32 v71, vcc, -1, v173, vcc
	global_load_dwordx4 v[134:137], v[70:71], off
	v_add_co_u32_e32 v70, vcc, 0xffffc000, v174
	s_lshl_b64 s[0:1], s[18:19], 1
	s_nop 0
	v_addc_co_u32_e32 v71, vcc, -1, v175, vcc
	v_lshl_add_u64 v[66:67], v[168:169], 0, s[0:1]
	v_lshl_add_u64 v[68:69], v[170:171], 0, s[0:1]
	global_load_dwordx4 v[138:141], v[70:71], off
	global_load_dwordx4 v[142:145], v[66:67], off
	global_load_dwordx4 v[146:149], v[68:69], off
.LBB0_163:
	s_add_i32 s11, s13, -3
	s_cmp_lt_u32 s11, 32
	s_cselect_b64 vcc, -1, 0
	s_cmp_lt_u32 s11, 64
	s_cselect_b64 s[0:1], -1, 0
	s_cmpk_lt_u32 s11, 0x60
	s_cselect_b64 s[8:9], -1, 0
	v_cndmask_b32_e64 v66, v117, v116, s[8:9]
	v_cndmask_b32_e64 v66, v66, v115, s[0:1]
	v_cndmask_b32_e32 v201, v66, v114, vcc
	s_and_b32 s2, s11, 30
	v_lshrrev_b32_e32 v66, s2, v201
	v_and_b32_e32 v66, 1, v66
	v_cmp_eq_u32_e64 s[0:1], 1, v66
	v_bfe_u32 v66, v201, s2, 1
	v_cmp_ne_u32_e32 vcc, 0, v66
	s_cbranch_vccz .LBB0_181
	v_add_u32_e32 v200, s10, v192
	v_add_u32_e32 v200, 0xffffff5f, v200
	v_cmp_lt_i32_e32 vcc, s21, v200
	s_waitcnt lgkmcnt(2)
	v_mfma_f32_32x32x16_bf16 v[66:81], v[238:241], v[82:85], 0
	ds_read_b128 v[238:241], v181 offset:96
	s_waitcnt lgkmcnt(2)
	v_mfma_f32_32x32x16_bf16 v[66:81], v[242:245], v[86:89], v[66:81]
	ds_read_b128 v[242:245], v181 offset:128
	s_waitcnt lgkmcnt(2)
	v_mfma_f32_32x32x16_bf16 v[66:81], v[246:249], v[90:93], v[66:81]
	ds_read_b128 v[246:249], v181 offset:160
	s_waitcnt lgkmcnt(2)
	v_mfma_f32_32x32x16_bf16 v[66:81], v[238:241], v[94:97], v[66:81]
	ds_read_b128 v[238:241], v181 offset:192
	s_waitcnt lgkmcnt(2)
	v_mfma_f32_32x32x16_bf16 v[66:81], v[242:245], v[98:101], v[66:81]
	ds_read_b128 v[242:245], v181 offset:224
	s_waitcnt lgkmcnt(2)
	v_mfma_f32_32x32x16_bf16 v[66:81], v[246:249], v[102:105], v[66:81]
	s_waitcnt lgkmcnt(1)
	v_mfma_f32_32x32x16_bf16 v[66:81], v[238:241], v[106:109], v[66:81]
	s_waitcnt lgkmcnt(0)
	v_mfma_f32_32x32x16_bf16 v[66:81], v[242:245], v[110:113], v[66:81]
	s_and_saveexec_b64 s[2:3], vcc
	s_cbranch_execz .LBB0_166
	v_add_u32_e32 v200, s10, v161
	v_add_u32_e32 v202, 0xffffff40, v200
	v_cmp_le_i32_e32 vcc, v202, v0
	s_nop 6
	v_cndmask_b32_e32 v66, v209, v66, vcc
	v_cmp_lt_i32_e32 vcc, v202, v0
	v_add_u32_e32 v202, 0xffffff42, v200
	s_nop 0
	v_cndmask_b32_e32 v67, v209, v67, vcc
	v_cmp_le_i32_e32 vcc, v202, v0
	v_add_u32_e32 v202, 0xffffff43, v200
	s_nop 0
	v_cndmask_b32_e32 v68, v209, v68, vcc
	v_cmp_le_i32_e32 vcc, v202, v0
	v_add_u32_e32 v202, 0xffffff48, v200
	s_nop 0
	v_cndmask_b32_e32 v69, v209, v69, vcc
	v_cmp_le_i32_e32 vcc, v202, v0
	v_add_u32_e32 v202, 0xffffff49, v200
	s_nop 0
	v_cndmask_b32_e32 v70, v209, v70, vcc
	v_cmp_le_i32_e32 vcc, v202, v0
	v_add_u32_e32 v202, 0xffffff4a, v200
	s_nop 0
	v_cndmask_b32_e32 v71, v209, v71, vcc
	v_cmp_le_i32_e32 vcc, v202, v0
	v_add_u32_e32 v202, 0xffffff4b, v200
	s_nop 0
	v_cndmask_b32_e32 v72, v209, v72, vcc
	v_cmp_le_i32_e32 vcc, v202, v0
	v_add_u32_e32 v202, 0xffffff50, v200
	s_nop 0
	v_cndmask_b32_e32 v73, v209, v73, vcc
	v_cmp_le_i32_e32 vcc, v202, v0
	v_add_u32_e32 v202, 0xffffff51, v200
	s_nop 0
	v_cndmask_b32_e32 v74, v209, v74, vcc
	v_cmp_le_i32_e32 vcc, v202, v0
	v_add_u32_e32 v202, 0xffffff52, v200
	s_nop 0
	v_cndmask_b32_e32 v75, v209, v75, vcc
	v_cmp_le_i32_e32 vcc, v202, v0
	v_add_u32_e32 v202, 0xffffff53, v200
	s_nop 0
	v_cndmask_b32_e32 v76, v209, v76, vcc
	v_cmp_le_i32_e32 vcc, v202, v0
	v_add_u32_e32 v202, 0xffffff58, v200
	s_nop 0
	v_cndmask_b32_e32 v77, v209, v77, vcc
	v_cmp_le_i32_e32 vcc, v202, v0
	v_add_u32_e32 v202, 0xffffff59, v200
	s_nop 0
	v_cndmask_b32_e32 v78, v209, v78, vcc
	v_cmp_le_i32_e32 vcc, v202, v0
	v_add_u32_e32 v202, 0xffffff5a, v200
	v_add_u32_e32 v200, 0xffffff5b, v200
	v_cndmask_b32_e32 v79, v209, v79, vcc
	v_cmp_le_i32_e32 vcc, v202, v0
	s_nop 1
	v_cndmask_b32_e32 v80, v209, v80, vcc
	v_cmp_le_i32_e32 vcc, v200, v0
	s_nop 1
	v_cndmask_b32_e32 v81, v209, v81, vcc

; DI int crow(int i, int h) { return (i & 3) + 8 * (i >> 2) + 4 * h; }
; template <int MODE> ...
;     ...
;   auto body = [&](const int kb, const char* Ks, const char* Vs) {
;     bool bit = true;
;     if (MODE == 2) { unsigned w = (kb < 32) ? s0 : (kb < 64) ? s1 : (kb < 96) ? s2 : s3; bit = ((w >> (kb & 31)) & 1u) != 0; }
;     if (MODE != 2 || __any(bit)) {
;       f32x16 acc = scores_lds(Ks, half, qf, r, h);
;       const int key0 = kb * 64 + half * 32;
;       bool full;
;       if (MODE <= 1) full = (16 * (key0 + 31) + 31) <= t0;
;       else if (MODE == 2) full = (key0 + 31) <= t0;
;       else full = ((key0 + 31) <= t0) && (key0 >= (t0 + 31 - 511));
;       if (!full) {
; #pragma unroll
;         for (int i = 0; i < 16; ++i) {
;           const int key = key0 + crow(i, h);
;           bool v;
;           if (MODE <= 1) v = (16 * key + 31) <= t; else if (MODE == 2) v = key <= t; else v = (key <= t) && ((t - key) < 512);
;           acc[i] = v ? acc[i] : -1e30f;
;         }
;     ...
;   while (true) {
;     if (kb + 2 <= kb1) stage_load<NEEDV>(sr2, K, VT, ldvt, kb + 2, tid);
;     body(kb, buf0, buf0 + KS_BYTES);
;     if (kb < kb1) stage_store<NEEDV>(sr, buf1, buf1 + KS_BYTES, tid);
.LBB0_170:
	s_andn2_b64 vcc, exec, s[0:1]
	s_mov_b64 s[0:1], -1
	s_waitcnt lgkmcnt(0)
	s_barrier
	s_cbranch_vccnz .LBB0_160
	v_add_u32_e32 v237, v180, v150
	ds_read_b128 v[238:241], v237
	ds_read_b128 v[242:245], v237 offset:32
	ds_read_b128 v[246:249], v237 offset:64
	s_cmp_gt_u32 s13, s12
	s_cbranch_scc1 .LBB0_173
	s_mov_b32 s11, s19
	s_lshl_b64 s[0:1], s[10:11], 1
	v_lshl_add_u64 v[66:67], v[168:169], 0, s[0:1]
	v_lshl_add_u64 v[68:69], v[170:171], 0, s[0:1]
	global_load_dwordx4 v[118:121], v[172:173], off
	global_load_dwordx4 v[122:125], v[174:175], off
	global_load_dwordx4 v[126:129], v[66:67], off
	global_load_dwordx4 v[130:133], v[68:69], off
.LBB0_173:
	s_add_i32 s8, s13, -2
	v_lshrrev_b32_e32 v66, s8, v201
	s_and_b32 s2, s8, 31
	v_and_b32_e32 v66, 1, v66
	v_cmp_eq_u32_e64 s[0:1], 1, v66
	v_bfe_u32 v66, v201, s2, 1
	v_cmp_ne_u32_e32 vcc, 0, v66
	s_cbranch_vccz .LBB0_182
	v_add_u32_e32 v166, v180, v150
	s_waitcnt lgkmcnt(2)
	v_mfma_f32_32x32x16_bf16 v[66:81], v[238:241], v[82:85], 0
	ds_read_b128 v[238:241], v166 offset:96
	s_waitcnt lgkmcnt(2)
	v_mfma_f32_32x32x16_bf16 v[66:81], v[242:245], v[86:89], v[66:81]
	ds_read_b128 v[242:245], v166 offset:128
	s_waitcnt lgkmcnt(2)
	v_mfma_f32_32x32x16_bf16 v[66:81], v[246:249], v[90:93], v[66:81]
	ds_read_b128 v[246:249], v166 offset:160
	s_waitcnt lgkmcnt(2)
	v_mfma_f32_32x32x16_bf16 v[66:81], v[238:241], v[94:97], v[66:81]
	ds_read_b128 v[238:241], v166 offset:192
	s_waitcnt lgkmcnt(2)
	v_mfma_f32_32x32x16_bf16 v[66:81], v[242:245], v[98:101], v[66:81]
	ds_read_b128 v[242:245], v166 offset:224
	s_waitcnt lgkmcnt(2)
	v_mfma_f32_32x32x16_bf16 v[66:81], v[246:249], v[102:105], v[66:81]
	s_waitcnt lgkmcnt(1)
	v_mfma_f32_32x32x16_bf16 v[66:81], v[238:241], v[106:109], v[66:81]
	v_add_u32_e32 v166, s10, v192
	v_add_u32_e32 v166, 0xffffff9f, v166
	v_cmp_lt_i32_e32 vcc, s21, v166
	s_waitcnt lgkmcnt(0)
	v_mfma_f32_32x32x16_bf16 v[66:81], v[242:245], v[110:113], v[66:81]
	s_and_saveexec_b64 s[2:3], vcc
	s_cbranch_execz .LBB0_176
	v_add_u32_e32 v166, s10, v161
	v_add_u32_e32 v201, 0xffffff80, v166
	v_cmp_le_i32_e32 vcc, v201, v0
	s_nop 6
	v_cndmask_b32_e32 v66, v209, v66, vcc
	v_cmp_lt_i32_e32 vcc, v201, v0
	v_add_u32_e32 v201, 0xffffff82, v166
	s_nop 0
	v_cndmask_b32_e32 v67, v209, v67, vcc
	v_cmp_le_i32_e32 vcc, v201, v0
	v_add_u32_e32 v201, 0xffffff83, v166
	s_nop 0
	v_cndmask_b32_e32 v68, v209, v68, vcc
	v_cmp_le_i32_e32 vcc, v201, v0
	v_add_u32_e32 v201, 0xffffff88, v166
	s_nop 0
	v_cndmask_b32_e32 v69, v209, v69, vcc
	v_cmp_le_i32_e32 vcc, v201, v0
	v_add_u32_e32 v201, 0xffffff89, v166
	s_nop 0
	v_cndmask_b32_e32 v70, v209, v70, vcc
	v_cmp_le_i32_e32 vcc, v201, v0
	v_add_u32_e32 v201, 0xffffff8a, v166
	s_nop 0
	v_cndmask_b32_e32 v71, v209, v71, vcc
	v_cmp_le_i32_e32 vcc, v201, v0
	v_add_u32_e32 v201, 0xffffff8b, v166
	s_nop 0
	v_cndmask_b32_e32 v72, v209, v72, vcc
	v_cmp_le_i32_e32 vcc, v201, v0
	v_add_u32_e32 v201, 0xffffff90, v166
	s_nop 0
	v_cndmask_b32_e32 v73, v209, v73, vcc
	v_cmp_le_i32_e32 vcc, v201, v0
	v_add_u32_e32 v201, 0xffffff91, v166
	s_nop 0
	v_cndmask_b32_e32 v74, v209, v74, vcc
	v_cmp_le_i32_e32 vcc, v201, v0
	v_add_u32_e32 v201, 0xffffff92, v166
	s_nop 0
	v_cndmask_b32_e32 v75, v209, v75, vcc
	v_cmp_le_i32_e32 vcc, v201, v0
	v_add_u32_e32 v201, 0xffffff93, v166
	s_nop 0
	v_cndmask_b32_e32 v76, v209, v76, vcc
	v_cmp_le_i32_e32 vcc, v201, v0
	v_add_u32_e32 v201, 0xffffff98, v166
	s_nop 0
	v_cndmask_b32_e32 v77, v209, v77, vcc
	v_cmp_le_i32_e32 vcc, v201, v0
	v_add_u32_e32 v201, 0xffffff99, v166
	s_nop 0
	v_cndmask_b32_e32 v78, v209, v78, vcc
	v_cmp_le_i32_e32 vcc, v201, v0
	v_add_u32_e32 v201, 0xffffff9a, v166
	v_add_u32_e32 v166, 0xffffff9b, v166
	v_cndmask_b32_e32 v79, v209, v79, vcc
	v_cmp_le_i32_e32 vcc, v201, v0
	s_nop 1
	v_cndmask_b32_e32 v80, v209, v80, vcc
	v_cmp_le_i32_e32 vcc, v166, v0
	s_nop 1
	v_cndmask_b32_e32 v81, v209, v81, vcc
